# speedup vs baseline: 1.0107x; 1.0022x over previous
; #define SLOAD(i, k0) do { const unsigned o0_ = soff0 + (unsigned)(k0) * (DM * 2u), o1_ = o0_ + 32u * DM * 2u;                 \
;     sr_[i].vs0 = *(const bf16x8*)((const char*)Vh + (size_t)o0_); sr_[i].vs1 = *(const bf16x8*)((const char*)Vh + (size_t)o1_); \
;     sr_[i].ks0 = *(const bf16x8*)((const char*)Kh + (size_t)o0_); sr_[i].ks1 = *(const bf16x8*)((const char*)Kh + (size_t)o1_); } while (0)
; #define SWRITE(boff, i) do { *(bf16x8*)(V_lds + (boff) + vst0) = sr_[i].vs0;          \
;     *(bf16x8*)(V_lds + (boff) + vst1) = sr_[i].vs1; int kc = sc * 2;               \
;     *(bf16x8*)(K_lds + (boff) + KSWZ(sr, kc)) = sr_[i].ks0;                       \
;     *(bf16x8*)(K_lds + (boff) + KSWZ(32 + sr, kc)) = sr_[i].ks1; } while (0)
; __device__ __forceinline__ void da_qkt(f32x16& p0, f32x16& p1, const char* Ks, const bf16x8* qr, int r32, int hi, int cbyte0) {
;   p0 = f32x16{}; p1 = f32x16{};
; #pragma unroll
;   for (int d0 = 0; d0 < 4; ++d0) {
;     int cbb = cbyte0 + (d0 * 16 + hi * 8) * 2;
;     bf16x8 b0 = *(const bf16x8*)(Ks + KSWZ(r32, cbb));
;     bf16x8 b1 = *(const bf16x8*)(Ks + KSWZ(32 + r32, cbb));
;     p0 = __builtin_amdgcn_mfma_f32_32x32x16_bf16(b0, qr[d0], p0, 0, 0, 0);
;     p1 = __builtin_amdgcn_mfma_f32_32x32x16_bf16(b1, qr[d0], p1, 0, 0, 0);
;   }
; }
; __device__ __forceinline__ void diff_block(const Params& p, int s, int h, int qb, char* lds, float lam_full, u16* Odst) {
;     ...
;   {
;     const bf16x8 zero8 = {0, 0, 0, 0, 0, 0, 0, 0};
;     sr_[SO].vs0 = zero8; sr_[SO].vs1 = zero8; sr_[SO].ks0 = zero8; sr_[SO].ks1 = zero8;
;     if (sr < 16) {
;       sr_[SO].ks0 = *(const bf16x8*)(Kp + (long)(NREAL + sr) * DM + h * 128 + sc);
;       sr_[SO].vs0 = *(const bf16x8*)(Vp + (long)(NREAL + sr) * DM + h * 128 + sc);
;     }
;     SLOAD(SE, 0);
;     __syncthreads();
;     SWRITE(2 * SHM_V, SO);
;     __syncthreads();
;     da_qkt(pA0, pA1, K_lds + 2 * SHM_K, qr, r32, hi, cbyte0);
; #pragma unroll
;     for (int r = 8; r < 16; ++r) pA0[r] = -1e30f;
; #pragma unroll
;     for (int r = 0; r < 16; ++r) pA1[r] = -1e30f;
;     da_partialSM(pA0, pA1, m_reg, mnA, alA);
;     da_finishSM(pA0, pA1, alA, l_reg, pa0, pa1, pa2, pa3);
;     da_pv(o, vb0 + 2 * SHM_V, pa0, pa1, pa2, pa3);
.LBB0_233:
	s_or_b64 exec, exec, s[2:3]
	v_and_b32_e32 v9, 0xfffff0, v8
	v_lshlrev_b32_e32 v11, 1, v8
	v_and_or_b32 v9, v11, 8, v9
	s_ashr_i32 s1, s0, 31
	v_lshrrev_b32_e32 v11, 1, v8
	v_lshrrev_b32_e32 v9, 1, v9
	v_lshrrev_b32_e32 v10, 5, v10
	v_and_b32_e32 v12, 3, v8
	s_lshl_b64 s[0:1], s[0:1], 11
	v_readlane_b32 s2, v254, 14
	v_or_b32_e32 v9, v9, v10
	v_and_or_b32 v11, v11, 4, v12
	v_readlane_b32 s3, v254, 15
	s_add_u32 s2, s2, s0
	v_lshlrev_b32_e32 v9, 9, v9
	v_lshlrev_b32_e32 v11, 6, v11
	v_and_b32_e32 v12, 48, v130
	s_addc_u32 s3, s3, s1
	v_or3_b32 v216, v9, v11, v12
	v_add_u32_e32 v9, 32, v8
	s_add_u32 s2, s2, s24
	v_and_b32_e32 v13, 0xfffff0, v9
	v_lshlrev_b32_e32 v14, 1, v9
	s_addc_u32 s3, s3, 0
	v_readlane_b32 s4, v254, 16
	v_and_or_b32 v13, v14, 8, v13
	v_readlane_b32 s5, v254, 17
	s_add_u32 s0, s4, s0
	v_lshrrev_b32_e32 v13, 1, v13
	s_addc_u32 s1, s5, s1
	v_or_b32_e32 v10, v13, v10
	s_add_u32 s8, s0, s24
	v_lshlrev_b32_e32 v131, 11, v8
	v_lshlrev_b32_e32 v10, 9, v10
	s_addc_u32 s9, s1, 0
	v_or_b32_e32 v118, v130, v131
	v_or3_b32 v217, v10, v11, v12
	v_add_u32_e32 v10, 0x10000, v118
	global_load_dwordx4 v[64:67], v118, s[8:9]
	global_load_dwordx4 v[68:71], v118, s[2:3]
	global_load_dwordx4 v[76:79], v10, s[8:9]
	global_load_dwordx4 v[72:75], v10, s[2:3]
	s_barrier
	s_waitcnt vmcnt(4)
	ds_write_b128 v216, v[4:7] offset:32768
	s_mov_b32 s6, s25
	s_mov_b32 s7, s25
	v_lshlrev_b32_e32 v4, 8, v8
	v_and_b32_e32 v5, 0x70, v115
	s_mov_b32 s4, s25
	s_mov_b32 s5, s25
	v_mov_b64_e32 v[12:13], s[6:7]
	v_bitop3_b32 v221, v130, v4, v5 bitop3:0xde
	v_mov_b64_e32 v[10:11], s[4:5]
	v_add_u32_e32 v4, 0x14000, v221
	ds_write_b128 v217, v[10:13] offset:32768
	ds_write_b128 v4, v[0:3]
	v_lshlrev_b32_e32 v0, 8, v9
	v_bitop3_b32 v222, v130, v0, v5 bitop3:0xde
	v_add_u32_e32 v0, 0x14000, v222
	ds_write_b128 v0, v[10:13]
	v_and_b32_e32 v229, 0x13, v207
	v_and_b32_e32 v230, 4, v207
	v_lshl_or_b32 v229, v230, 1, v229
	v_and_b32_e32 v230, 8, v207
	v_lshrrev_b32_e32 v230, 1, v230
	v_or_b32_e32 v229, v229, v230
	v_lshlrev_b32_e32 v0, 4, v229
	v_lshl_or_b32 v20, v211, 7, v96
	v_lshlrev_b32_e32 v21, 8, v229
	v_and_b32_e32 v22, 0x70, v0
	v_bitop3_b32 v223, v20, v21, v22 bitop3:0xde
	v_or_b32_e32 v0, 0x14000, v223
	s_waitcnt lgkmcnt(0)
	s_barrier
	ds_read_b128 v[0:3], v0
	v_or_b32_e32 v4, 32, v20
	v_bitop3_b32 v220, v4, v21, v22 bitop3:0xde
	v_or_b32_e32 v4, 0x14000, v220
	ds_read_b128 v[16:19], v4
	s_waitcnt lgkmcnt(1)
	v_mfma_f32_32x32x16_bf16 v[0:15], v[0:3], v[110:113], 0
	s_mov_b32 s0, 0xf149f2ca
	v_and_b32_e32 v132, 63, v115
	v_lshlrev_b32_e32 v24, 3, v132
	s_waitcnt lgkmcnt(0)
	v_mfma_f32_32x32x16_bf16 v[0:15], v[16:19], v[106:109], v[0:15]
	v_or_b32_e32 v16, 64, v20
	v_bitop3_b32 v219, v16, v21, v22 bitop3:0xde
	v_or_b32_e32 v16, 0x14000, v219
	ds_read_b128 v[16:19], v16
	v_or_b32_e32 v20, 0x60, v20
	v_bitop3_b32 v218, v20, v21, v22 bitop3:0xde
	v_or_b32_e32 v20, 0x14000, v218
	ds_read_b128 v[20:23], v20
	s_waitcnt lgkmcnt(1)
	v_mfma_f32_32x32x16_bf16 v[0:15], v[16:19], v[102:105], v[0:15]
	v_lshlrev_b32_e32 v16, 4, v132
	v_and_b32_e32 v16, 0xc0, v16
	v_lshlrev_b32_e32 v17, 1, v132
	v_and_or_b32 v16, v24, 24, v16
	v_and_b32_e32 v17, 32, v17
	v_and_b32_e32 v18, 0x100, v24
	v_or3_b32 v214, v16, v17, v18
	s_waitcnt lgkmcnt(0)
	v_mfma_f32_32x32x16_bf16 v[0:15], v[20:23], v[98:101], v[0:15]
	v_or_b32_e32 v128, 0x8000, v214
	s_nop 10
	v_max3_f32 v8, v0, v1, v2
	v_max3_f32 v8, v8, v3, v4
	v_max3_f32 v8, v8, v5, v6
	v_max3_f32 v8, v8, v7, s0
	v_mov_b32_e32 v9, v8
	s_nop 1
	v_permlane32_swap_b32_e32 v8, v9
	v_max_f32_e32 v9, v9, v9
	v_max_f32_e32 v8, v8, v8
	v_max_f32_e32 v8, v8, v9
	v_add_f32_e32 v9, 0x7149f2ca, v8
	s_mov_b32 s0, 0x42800000
	v_cmp_ge_f32_e32 vcc, s0, v9
	s_cmp_eq_u64 vcc, exec
	v_max_f32_e32 v116, 0xf149f2ca, v8
	s_cselect_b64 s[6:7], -1, 0
	v_cndmask_b32_e64 v213, v116, v194, s[6:7]
	v_mul_f32_e32 v114, 0xbe38aa3b, v213
	v_fmamk_f32 v0, v0, 0x3e38aa3b, v114
	v_fmamk_f32 v1, v1, 0x3e38aa3b, v114
	v_exp_f32_e32 v0, v0
	v_fmamk_f32 v2, v2, 0x3e38aa3b, v114
	v_exp_f32_e32 v1, v1
	v_fmamk_f32 v3, v3, 0x3e38aa3b, v114
	v_exp_f32_e32 v2, v2
	v_fmamk_f32 v4, v4, 0x3e38aa3b, v114
	v_exp_f32_e32 v3, v3
	v_fmamk_f32 v5, v5, 0x3e38aa3b, v114
	v_exp_f32_e32 v4, v4
	v_add_f32_e32 v9, 0, v0
	v_fmamk_f32 v6, v6, 0x3e38aa3b, v114
	v_exp_f32_e32 v5, v5
	v_add_f32_e32 v9, v1, v9
	v_fmamk_f32 v7, v7, 0x3e38aa3b, v114
	v_mov_b32_e32 v8, 0x3e38aa3b
	v_exp_f32_e32 v6, v6
	v_add_f32_e32 v9, v2, v9
	v_fmamk_f32 v8, v8, 0xf149f2ca, v114
	v_exp_f32_e32 v7, v7
	v_add_f32_e32 v9, v3, v9
	v_exp_f32_e32 v8, v8
	v_add_f32_e32 v9, v4, v9
	v_add_f32_e32 v9, v5, v9
	v_add_f32_e32 v9, v6, v9
	v_add_f32_e32 v9, v7, v9
	v_add_f32_e32 v9, v8, v9
	v_add_f32_e32 v9, v8, v9
	v_add_f32_e32 v9, v8, v9
	v_add_f32_e32 v9, v8, v9
	v_add_f32_e32 v9, v8, v9
	v_add_f32_e32 v9, v8, v9
	v_add_f32_e32 v9, v8, v9
	v_add_f32_e32 v9, v8, v9
	v_add_f32_e32 v9, v8, v9
	v_add_f32_e32 v9, v8, v9
	v_add_f32_e32 v9, v8, v9
	v_add_f32_e32 v9, v8, v9
	v_add_f32_e32 v9, v8, v9
	v_add_f32_e32 v9, v8, v9
	v_add_f32_e32 v9, v8, v9
	v_add_f32_e32 v9, v8, v9
	v_cvt_pk_bf16_f32 v48, v0, v1
	v_cvt_pk_bf16_f32 v49, v2, v3
	v_cvt_pk_bf16_f32 v50, v4, v5
	v_cvt_pk_bf16_f32 v51, v6, v7
	v_cvt_pk_bf16_f32 v80, v8, v8
	v_cvt_pk_bf16_f32 v81, v8, v8
	v_cvt_pk_bf16_f32 v82, v8, v8
	v_cvt_pk_bf16_f32 v83, v8, v8
	v_cvt_pk_bf16_f32 v84, v8, v8
	v_cvt_pk_bf16_f32 v85, v8, v8
	v_cvt_pk_bf16_f32 v86, v8, v8
	v_cvt_pk_bf16_f32 v87, v8, v8
	v_cvt_pk_bf16_f32 v88, v8, v8
	v_cvt_pk_bf16_f32 v89, v8, v8
	v_cvt_pk_bf16_f32 v90, v8, v8
	v_cvt_pk_bf16_f32 v91, v8, v8
	ds_read_b64_tr_b16 v[0:1], v128 offset:0
	v_add_f32_e32 v9, v8, v9
	ds_read_b64_tr_b16 v[2:3], v128 offset:0x800
	v_add_f32_e32 v9, v8, v9
	ds_read_b64_tr_b16 v[16:17], v128 offset:0x1000
	v_add_f32_e32 v9, v8, v9
	ds_read_b64_tr_b16 v[18:19], v128 offset:0x1800
	v_add_f32_e32 v9, v8, v9
	ds_read_b64_tr_b16 v[20:21], v128 offset:0x2000
	v_add_f32_e32 v9, v8, v9
	ds_read_b64_tr_b16 v[22:23], v128 offset:0x2800
	v_add_f32_e32 v9, v8, v9
	ds_read_b64_tr_b16 v[24:25], v128 offset:0x3000
	v_add_f32_e32 v9, v8, v9
	ds_read_b64_tr_b16 v[26:27], v128 offset:0x3800
	v_add_f32_e32 v117, v8, v9
	s_waitcnt lgkmcnt(0)
; #define SBAR() __builtin_amdgcn_sched_barrier(0)
; #define SWRITE(boff, i) do { *(bf16x8*)(V_lds + (boff) + vst0) = sr_[i].vs0;          \
;     *(bf16x8*)(V_lds + (boff) + vst1) = sr_[i].vs1; int kc = sc * 2;               \
;     *(bf16x8*)(K_lds + (boff) + KSWZ(sr, kc)) = sr_[i].ks0;                       \
;     *(bf16x8*)(K_lds + (boff) + KSWZ(32 + sr, kc)) = sr_[i].ks1; } while (0)
; template <int D0> __device__ __forceinline__ void pv_one(f32x16& od, int vb, bf16x8 pa0, bf16x8 pa1, bf16x8 pa2, bf16x8 pa3) {
;   const s16x4 l0 = tr_read<v_rd_off(D0, 0, 0)>(vb), h0 = tr_read<v_rd_off(D0, 0, 1)>(vb), l1 = tr_read<v_rd_off(D0, 1, 0)>(vb), h1 = tr_read<v_rd_off(D0, 1, 1)>(vb);
;   const s16x4 l2 = tr_read<v_rd_off(D0, 2, 0)>(vb), h2 = tr_read<v_rd_off(D0, 2, 1)>(vb), l3 = tr_read<v_rd_off(D0, 3, 0)>(vb), h3 = tr_read<v_rd_off(D0, 3, 1)>(vb);
;   asm volatile("s_waitcnt lgkmcnt(0)" ::: "memory"); SBAR();
;     ...
;   od = __builtin_amdgcn_mfma_f32_32x32x16_bf16(pa0, PK(l0, h0), od, 0, 0, 0);
;   od = __builtin_amdgcn_mfma_f32_32x32x16_bf16(pa1, PK(l1, h1), od, 0, 0, 0);
;   od = __builtin_amdgcn_mfma_f32_32x32x16_bf16(pa2, PK(l2, h2), od, 0, 0, 0);
;   od = __builtin_amdgcn_mfma_f32_32x32x16_bf16(pa3, PK(l3, h3), od, 0, 0, 0);
; __device__ __forceinline__ void diff_block(const Params& p, int s, int h, int qb, char* lds, float lam_full, u16* Odst) {
;     ...
;     da_pv(o, vb0 + 2 * SHM_V, pa0, pa1, pa2, pa3);
;   }
;   asm volatile("s_waitcnt vmcnt(0)" ::: "memory"); SWRITE(0, SE); __syncthreads();
;   da_qkt(pA0, pA1, K_lds, qr, r32, hi, cbyte0); da_partialSM(pA0, pA1, m_reg, mnA, alA);
	v_mov_b32_e32 v119, v117
	s_nop 1
	v_permlane32_swap_b32_e32 v117, v119
	v_mfma_f32_32x32x16_bf16 v[0:15], v[48:51], v[0:3], 0
	v_mfma_f32_32x32x16_bf16 v[0:15], v[80:83], v[16:19], v[0:15]
	ds_read_b64_tr_b16 v[16:17], v128 offset:0x200
	ds_read_b64_tr_b16 v[18:19], v128 offset:0xa00
	ds_read_b64_tr_b16 v[32:33], v128 offset:0x1200
	ds_read_b64_tr_b16 v[34:35], v128 offset:0x1a00
	ds_read_b64_tr_b16 v[36:37], v128 offset:0x2200
	ds_read_b64_tr_b16 v[38:39], v128 offset:0x2a00
	ds_read_b64_tr_b16 v[40:41], v128 offset:0x3200
	v_mfma_f32_32x32x16_bf16 v[0:15], v[84:87], v[20:23], v[0:15]
	ds_read_b64_tr_b16 v[42:43], v128 offset:0x3a00
	s_waitcnt lgkmcnt(0)
	v_mfma_f32_32x32x16_bf16 v[0:15], v[88:91], v[24:27], v[0:15]
	v_mfma_f32_32x32x16_bf16 v[16:31], v[48:51], v[16:19], 0
	v_mfma_f32_32x32x16_bf16 v[16:31], v[80:83], v[32:35], v[16:31]
	ds_read_b64_tr_b16 v[32:33], v128 offset:0x400
	ds_read_b64_tr_b16 v[34:35], v128 offset:0xc00
	ds_read_b64_tr_b16 v[52:53], v128 offset:0x1400
	ds_read_b64_tr_b16 v[54:55], v128 offset:0x1c00
	ds_read_b64_tr_b16 v[56:57], v128 offset:0x2400
	ds_read_b64_tr_b16 v[58:59], v128 offset:0x2c00
	ds_read_b64_tr_b16 v[60:61], v128 offset:0x3400
	v_mfma_f32_32x32x16_bf16 v[16:31], v[84:87], v[36:39], v[16:31]
	ds_read_b64_tr_b16 v[62:63], v128 offset:0x3c00
	s_waitcnt lgkmcnt(0)
	v_mfma_f32_32x32x16_bf16 v[16:31], v[88:91], v[40:43], v[16:31]
	v_mfma_f32_32x32x16_bf16 v[32:47], v[48:51], v[32:35], 0
	v_mfma_f32_32x32x16_bf16 v[32:47], v[80:83], v[52:55], v[32:47]
	ds_read_b64_tr_b16 v[52:53], v128 offset:0x600
	ds_read_b64_tr_b16 v[54:55], v128 offset:0xe00
	ds_read_b64_tr_b16 v[92:93], v128 offset:0x1600
	ds_read_b64_tr_b16 v[94:95], v128 offset:0x1e00
	ds_read_b64_tr_b16 v[120:121], v128 offset:0x2600
	ds_read_b64_tr_b16 v[122:123], v128 offset:0x2e00
	ds_read_b64_tr_b16 v[124:125], v128 offset:0x3600
	v_mfma_f32_32x32x16_bf16 v[32:47], v[84:87], v[56:59], v[32:47]
	ds_read_b64_tr_b16 v[126:127], v128 offset:0x3e00
	s_waitcnt lgkmcnt(0)
	v_mfma_f32_32x32x16_bf16 v[32:47], v[88:91], v[60:63], v[32:47]
	v_mfma_f32_32x32x16_bf16 v[48:63], v[48:51], v[52:55], 0
	s_waitcnt vmcnt(0)
	s_waitcnt vmcnt(3)
	ds_write_b128 v216, v[64:67]
	s_waitcnt vmcnt(1)
	ds_write_b128 v217, v[76:79]
	ds_write_b128 v221, v[68:71] offset:49152
	s_waitcnt vmcnt(0)
	ds_write_b128 v222, v[72:75] offset:49152
	s_waitcnt lgkmcnt(0)
	s_barrier
	ds_read_b128 v[64:67], v223 offset:49152
	ds_read_b128 v[68:71], v223 offset:57344
	v_mfma_f32_32x32x16_bf16 v[48:63], v[80:83], v[92:95], v[48:63]
	v_mfma_f32_32x32x16_bf16 v[48:63], v[84:87], v[120:123], v[48:63]
	v_mfma_f32_32x32x16_bf16 v[48:63], v[88:91], v[124:127], v[48:63]
	ds_read_b128 v[120:123], v220 offset:49152
	ds_read_b128 v[124:127], v220 offset:57344
	s_waitcnt lgkmcnt(3)
	v_mfma_f32_32x32x16_bf16 v[80:95], v[64:67], v[110:113], 0
	s_waitcnt lgkmcnt(2)
	v_mfma_f32_32x32x16_bf16 v[64:79], v[68:71], v[110:113], 0
	s_waitcnt lgkmcnt(1)
	v_mfma_f32_32x32x16_bf16 v[80:95], v[120:123], v[106:109], v[80:95]
	s_waitcnt lgkmcnt(0)
	v_mfma_f32_32x32x16_bf16 v[64:79], v[124:127], v[106:109], v[64:79]
	ds_read_b128 v[120:123], v219 offset:49152
	ds_read_b128 v[124:127], v219 offset:57344
	s_waitcnt lgkmcnt(1)
	v_mfma_f32_32x32x16_bf16 v[80:95], v[120:123], v[102:105], v[80:95]
	s_waitcnt lgkmcnt(0)
	v_mfma_f32_32x32x16_bf16 v[64:79], v[124:127], v[102:105], v[64:79]
	ds_read_b128 v[120:123], v218 offset:49152
	ds_read_b128 v[124:127], v218 offset:57344
	s_waitcnt lgkmcnt(1)
	v_mfma_f32_32x32x16_bf16 v[80:95], v[120:123], v[98:101], v[80:95]
	s_waitcnt lgkmcnt(0)
	v_mfma_f32_32x32x16_bf16 v[64:79], v[124:127], v[98:101], v[64:79]
	s_nop 9
	v_max_f32_e32 v120, v81, v81
	v_max_f32_e32 v121, v80, v80
	v_max_f32_e32 v120, v121, v120
	v_max3_f32 v120, v120, v82, v83
	v_max3_f32 v120, v120, v84, v85
	v_max3_f32 v120, v120, v86, v87
	v_max3_f32 v120, v120, v88, v89
	v_max3_f32 v120, v120, v90, v91
	v_max3_f32 v120, v120, v92, v93
	v_max3_f32 v120, v120, v94, v95
	v_max3_f32 v120, v120, v64, v65
	v_max3_f32 v120, v120, v66, v67
	v_max3_f32 v120, v120, v68, v69
	v_max3_f32 v120, v120, v70, v71
	v_max3_f32 v120, v120, v72, v73
	v_max3_f32 v120, v120, v74, v75
	v_max3_f32 v120, v120, v76, v77
	v_max3_f32 v120, v120, v78, v79
	v_mov_b32_e32 v121, v120
	s_nop 1
	v_permlane32_swap_b32_e32 v120, v121
	v_max_f32_e32 v121, v121, v121
	v_max_f32_e32 v120, v120, v120
	v_max_f32_e32 v121, v120, v121
	v_sub_f32_e32 v120, v121, v213
	v_cmp_ge_f32_e32 vcc, s0, v120
	v_mov_b32_e32 v120, 1.0
	s_cmp_eq_u64 vcc, exec
	s_cbranch_scc0 .LBB0_274

; __device__ __forceinline__ void da_finish2(f32x16& p0, f32x16& p1, float& m_reg, float& l_reg, float& alpha,
;                                            bf16x8& pa0, bf16x8& pa1, bf16x8& pa2, bf16x8& pa3) {
;     ...
;   PK4(p0, 0, pa0); PK4(p0, 8, pa1); PK4(p1, 0, pa2); PK4(p1, 8, pa3);
.LBB0_240:
	v_cvt_pk_bf16_f32 v146, v146, v147
	v_cvt_pk_bf16_f32 v147, v148, v149
	v_cvt_pk_bf16_f32 v148, v150, v151
	v_cvt_pk_bf16_f32 v149, v160, v161
	v_cvt_pk_bf16_f32 v150, v158, v159
	v_cvt_pk_bf16_f32 v151, v156, v157
	v_cvt_pk_bf16_f32 v152, v152, v153
	v_cvt_pk_bf16_f32 v153, v154, v155
	v_cvt_pk_bf16_f32 v154, v130, v131
	v_cvt_pk_bf16_f32 v155, v132, v133
	v_cvt_pk_bf16_f32 v156, v134, v135
	v_cvt_pk_bf16_f32 v157, v138, v139
	v_cvt_pk_bf16_f32 v158, v136, v137
	v_cvt_pk_bf16_f32 v159, v140, v141
	v_cvt_pk_bf16_f32 v160, v142, v143
	v_cvt_pk_bf16_f32 v161, v144, v145
	s_nop 0
	v_cmp_gt_f32_e32 vcc, 1.0, v164
	s_cbranch_vccz .LBB0_244
	s_and_saveexec_b64 s[0:1], s[6:7]
	ds_write_b32 v215, v164 offset:128
	s_or_b64 exec, exec, s[0:1]
	s_waitcnt lgkmcnt(0)
	v_add_u32_e32 v142, v212, v96
	ds_read_b128 v[130:133], v142 offset:224
	ds_read_b128 v[134:137], v142 offset:192
	ds_read_b128 v[138:141], v142 offset:160
	ds_read_b128 v[142:145], v142 offset:128
	s_waitcnt lgkmcnt(3)
	v_pk_mul_f32 v[12:13], v[12:13], v[130:131]
	s_waitcnt lgkmcnt(2)
	v_pk_mul_f32 v[8:9], v[8:9], v[134:135]
	s_waitcnt lgkmcnt(1)
	v_pk_mul_f32 v[4:5], v[4:5], v[138:139]
	v_pk_mul_f32 v[14:15], v[14:15], v[132:133]
	v_pk_mul_f32 v[10:11], v[10:11], v[136:137]
	v_pk_mul_f32 v[6:7], v[6:7], v[140:141]
	s_waitcnt lgkmcnt(0)
	v_pk_mul_f32 v[2:3], v[2:3], v[144:145]
	v_pk_mul_f32 v[0:1], v[0:1], v[142:143]
	v_pk_mul_f32 v[28:29], v[28:29], v[130:131]
	v_pk_mul_f32 v[24:25], v[24:25], v[134:135]
	v_pk_mul_f32 v[20:21], v[20:21], v[138:139]
	v_pk_mul_f32 v[30:31], v[30:31], v[132:133]
	v_pk_mul_f32 v[26:27], v[26:27], v[136:137]
	v_pk_mul_f32 v[22:23], v[22:23], v[140:141]
	v_pk_mul_f32 v[18:19], v[18:19], v[144:145]
	v_pk_mul_f32 v[16:17], v[16:17], v[142:143]
	v_pk_mul_f32 v[44:45], v[44:45], v[130:131]
	v_pk_mul_f32 v[40:41], v[40:41], v[134:135]
	v_pk_mul_f32 v[36:37], v[36:37], v[138:139]
	v_pk_mul_f32 v[46:47], v[46:47], v[132:133]
	v_pk_mul_f32 v[42:43], v[42:43], v[136:137]
	v_pk_mul_f32 v[38:39], v[38:39], v[140:141]
	v_pk_mul_f32 v[34:35], v[34:35], v[144:145]
	v_pk_mul_f32 v[32:33], v[32:33], v[142:143]
	v_pk_mul_f32 v[60:61], v[60:61], v[130:131]
	v_pk_mul_f32 v[56:57], v[56:57], v[134:135]
	v_pk_mul_f32 v[52:53], v[52:53], v[138:139]
	v_pk_mul_f32 v[62:63], v[62:63], v[132:133]
	v_pk_mul_f32 v[58:59], v[58:59], v[136:137]
	v_pk_mul_f32 v[54:55], v[54:55], v[140:141]
	v_pk_mul_f32 v[50:51], v[50:51], v[144:145]
	v_pk_mul_f32 v[48:49], v[48:49], v[142:143]

; __device__ __forceinline__ void da_finish2(f32x16& p0, f32x16& p1, float& m_reg, float& l_reg, float& alpha,
;                                            bf16x8& pa0, bf16x8& pa1, bf16x8& pa2, bf16x8& pa3) {
;     ...
;   PK4(p0, 0, pa0); PK4(p0, 8, pa1); PK4(p1, 0, pa2); PK4(p1, 8, pa3);
.LBB0_246:
	v_cvt_pk_bf16_f32 v146, v146, v147
	v_cvt_pk_bf16_f32 v147, v160, v161
	v_cvt_pk_bf16_f32 v148, v148, v149
	v_cvt_pk_bf16_f32 v149, v158, v159
	v_cvt_pk_bf16_f32 v150, v150, v151
	v_cvt_pk_bf16_f32 v151, v156, v157
	v_cvt_pk_bf16_f32 v152, v152, v153
	v_cvt_pk_bf16_f32 v153, v154, v155
	v_cvt_pk_bf16_f32 v154, v176, v177
	v_cvt_pk_bf16_f32 v155, v182, v183
	v_cvt_pk_bf16_f32 v156, v180, v181
	v_cvt_pk_bf16_f32 v157, v178, v179
	v_cvt_pk_bf16_f32 v158, v174, v175
	v_cvt_pk_bf16_f32 v159, v172, v173
	v_cvt_pk_bf16_f32 v160, v170, v171
	v_cvt_pk_bf16_f32 v161, v168, v169
	s_nop 0
	v_cmp_gt_f32_e32 vcc, 1.0, v166
	s_cbranch_vccz .LBB0_250
	s_and_saveexec_b64 s[0:1], s[6:7]
	ds_write_b32 v215, v166 offset:128
	s_or_b64 exec, exec, s[0:1]
	s_waitcnt lgkmcnt(0)
	v_add_u32_e32 v167, v212, v96
	ds_read_b128 v[168:171], v167 offset:224
	ds_read_b128 v[172:175], v167 offset:192
	ds_read_b128 v[176:179], v167 offset:160
	ds_read_b128 v[180:183], v167 offset:128
	s_waitcnt lgkmcnt(3)
	v_pk_mul_f32 v[12:13], v[12:13], v[168:169]
	s_waitcnt lgkmcnt(2)
	v_pk_mul_f32 v[8:9], v[8:9], v[172:173]
	s_waitcnt lgkmcnt(1)
	v_pk_mul_f32 v[4:5], v[4:5], v[176:177]
	v_pk_mul_f32 v[14:15], v[14:15], v[170:171]
	v_pk_mul_f32 v[10:11], v[10:11], v[174:175]
	v_pk_mul_f32 v[6:7], v[6:7], v[178:179]
	s_waitcnt lgkmcnt(0)
	v_pk_mul_f32 v[2:3], v[2:3], v[182:183]
	v_pk_mul_f32 v[0:1], v[0:1], v[180:181]
	v_pk_mul_f32 v[28:29], v[28:29], v[168:169]
	v_pk_mul_f32 v[24:25], v[24:25], v[172:173]
	v_pk_mul_f32 v[20:21], v[20:21], v[176:177]
	v_pk_mul_f32 v[30:31], v[30:31], v[170:171]
	v_pk_mul_f32 v[26:27], v[26:27], v[174:175]
	v_pk_mul_f32 v[22:23], v[22:23], v[178:179]
	v_pk_mul_f32 v[18:19], v[18:19], v[182:183]
	v_pk_mul_f32 v[16:17], v[16:17], v[180:181]
	v_pk_mul_f32 v[44:45], v[44:45], v[168:169]
	v_pk_mul_f32 v[40:41], v[40:41], v[172:173]
	v_pk_mul_f32 v[36:37], v[36:37], v[176:177]
	v_pk_mul_f32 v[46:47], v[46:47], v[170:171]
	v_pk_mul_f32 v[42:43], v[42:43], v[174:175]
	v_pk_mul_f32 v[38:39], v[38:39], v[178:179]
	v_pk_mul_f32 v[34:35], v[34:35], v[182:183]
	v_pk_mul_f32 v[32:33], v[32:33], v[180:181]
	v_pk_mul_f32 v[60:61], v[60:61], v[168:169]
	v_pk_mul_f32 v[56:57], v[56:57], v[172:173]
	v_pk_mul_f32 v[52:53], v[52:53], v[176:177]
	v_pk_mul_f32 v[62:63], v[62:63], v[170:171]
	v_pk_mul_f32 v[58:59], v[58:59], v[174:175]
	v_pk_mul_f32 v[54:55], v[54:55], v[178:179]
	v_pk_mul_f32 v[50:51], v[50:51], v[182:183]
	v_pk_mul_f32 v[48:49], v[48:49], v[180:181]

; __device__ __forceinline__ void da_finish2(f32x16& p0, f32x16& p1, float& m_reg, float& l_reg, float& alpha,
;                                            bf16x8& pa0, bf16x8& pa1, bf16x8& pa2, bf16x8& pa3) {
;     ...
;   PK4(p0, 0, pa0); PK4(p0, 8, pa1); PK4(p1, 0, pa2); PK4(p1, 8, pa3);
.LBB0_258:
	v_cvt_pk_bf16_f32 v98, v146, v147
	v_cvt_pk_bf16_f32 v99, v148, v149
	v_cvt_pk_bf16_f32 v100, v150, v151
	v_cvt_pk_bf16_f32 v101, v160, v161
	v_cvt_pk_bf16_f32 v102, v158, v159
	v_cvt_pk_bf16_f32 v103, v156, v157
	v_cvt_pk_bf16_f32 v104, v152, v153
	v_cvt_pk_bf16_f32 v105, v154, v155
	v_cvt_pk_bf16_f32 v106, v106, v107
	v_cvt_pk_bf16_f32 v107, v122, v123
	v_cvt_pk_bf16_f32 v108, v108, v109
	v_cvt_pk_bf16_f32 v109, v120, v121
	v_cvt_pk_bf16_f32 v110, v110, v111
	v_cvt_pk_bf16_f32 v111, v118, v119
	v_cvt_pk_bf16_f32 v112, v112, v113
	v_cvt_pk_bf16_f32 v113, v116, v117
	s_nop 0
	v_cmp_gt_f32_e32 vcc, 1.0, v114
	s_cbranch_vccz .LBB0_262
	s_and_saveexec_b64 s[0:1], s[6:7]
	ds_write_b32 v215, v114 offset:128
	s_or_b64 exec, exec, s[0:1]
	s_waitcnt lgkmcnt(0)
	v_add_u32_e32 v128, v212, v96
	ds_read_b128 v[116:119], v128 offset:224
	ds_read_b128 v[120:123], v128 offset:192
	ds_read_b128 v[124:127], v128 offset:160
	ds_read_b128 v[128:131], v128 offset:128
	s_waitcnt lgkmcnt(3)
	v_pk_mul_f32 v[12:13], v[12:13], v[116:117]
	s_waitcnt lgkmcnt(2)
	v_pk_mul_f32 v[8:9], v[8:9], v[120:121]
	s_waitcnt lgkmcnt(1)
	v_pk_mul_f32 v[4:5], v[4:5], v[124:125]
	v_pk_mul_f32 v[14:15], v[14:15], v[118:119]
	v_pk_mul_f32 v[10:11], v[10:11], v[122:123]
	v_pk_mul_f32 v[6:7], v[6:7], v[126:127]
	s_waitcnt lgkmcnt(0)
	v_pk_mul_f32 v[2:3], v[2:3], v[130:131]
	v_pk_mul_f32 v[0:1], v[0:1], v[128:129]
	v_pk_mul_f32 v[28:29], v[28:29], v[116:117]
	v_pk_mul_f32 v[24:25], v[24:25], v[120:121]
	v_pk_mul_f32 v[20:21], v[20:21], v[124:125]
	v_pk_mul_f32 v[30:31], v[30:31], v[118:119]
	v_pk_mul_f32 v[26:27], v[26:27], v[122:123]
	v_pk_mul_f32 v[22:23], v[22:23], v[126:127]
	v_pk_mul_f32 v[18:19], v[18:19], v[130:131]
	v_pk_mul_f32 v[16:17], v[16:17], v[128:129]
	v_pk_mul_f32 v[44:45], v[44:45], v[116:117]
	v_pk_mul_f32 v[40:41], v[40:41], v[120:121]
	v_pk_mul_f32 v[36:37], v[36:37], v[124:125]
	v_pk_mul_f32 v[46:47], v[46:47], v[118:119]
	v_pk_mul_f32 v[42:43], v[42:43], v[122:123]
	v_pk_mul_f32 v[38:39], v[38:39], v[126:127]
	v_pk_mul_f32 v[34:35], v[34:35], v[130:131]
	v_pk_mul_f32 v[32:33], v[32:33], v[128:129]
	v_pk_mul_f32 v[60:61], v[60:61], v[116:117]
	v_pk_mul_f32 v[56:57], v[56:57], v[120:121]
	v_pk_mul_f32 v[52:53], v[52:53], v[124:125]
	v_pk_mul_f32 v[62:63], v[62:63], v[118:119]
	v_pk_mul_f32 v[58:59], v[58:59], v[122:123]
	v_pk_mul_f32 v[54:55], v[54:55], v[126:127]
	v_pk_mul_f32 v[50:51], v[50:51], v[130:131]
	v_pk_mul_f32 v[48:49], v[48:49], v[128:129]

; __device__ __forceinline__ void da_finish2(f32x16& p0, f32x16& p1, float& m_reg, float& l_reg, float& alpha,
;                                            bf16x8& pa0, bf16x8& pa1, bf16x8& pa2, bf16x8& pa3) {
;     ...
;   PK4(p0, 0, pa0); PK4(p0, 8, pa1); PK4(p1, 0, pa2); PK4(p1, 8, pa3);
.LBB0_264:
	v_cvt_pk_bf16_f32 v64, v64, v65
	v_cvt_pk_bf16_f32 v65, v98, v99
	v_cvt_pk_bf16_f32 v66, v66, v67
	v_cvt_pk_bf16_f32 v67, v94, v95
	v_cvt_pk_bf16_f32 v68, v68, v69
	v_cvt_pk_bf16_f32 v69, v92, v93
	v_cvt_pk_bf16_f32 v70, v70, v71
	v_cvt_pk_bf16_f32 v71, v90, v91
	v_cvt_pk_bf16_f32 v72, v72, v73
	v_cvt_pk_bf16_f32 v73, v88, v89
	v_cvt_pk_bf16_f32 v74, v74, v75
	v_cvt_pk_bf16_f32 v75, v86, v87
	v_cvt_pk_bf16_f32 v76, v76, v77
	v_cvt_pk_bf16_f32 v77, v84, v85
	v_cvt_pk_bf16_f32 v78, v78, v79
	v_cvt_pk_bf16_f32 v79, v82, v83
	s_nop 0
	v_cmp_gt_f32_e32 vcc, 1.0, v80
	s_cbranch_vccz .LBB0_268
	s_and_saveexec_b64 s[0:1], s[6:7]
	ds_write_b32 v215, v80 offset:128
	s_or_b64 exec, exec, s[0:1]
	s_waitcnt lgkmcnt(0)
	v_add_u32_e32 v94, v212, v96
	ds_read_b128 v[82:85], v94 offset:224
	ds_read_b128 v[86:89], v94 offset:192
	ds_read_b128 v[90:93], v94 offset:160
	ds_read_b128 v[98:101], v94 offset:128
	s_waitcnt lgkmcnt(3)
	v_pk_mul_f32 v[12:13], v[12:13], v[82:83]
	s_waitcnt lgkmcnt(2)
	v_pk_mul_f32 v[8:9], v[8:9], v[86:87]
	s_waitcnt lgkmcnt(1)
	v_pk_mul_f32 v[4:5], v[4:5], v[90:91]
	v_pk_mul_f32 v[14:15], v[14:15], v[84:85]
	v_pk_mul_f32 v[10:11], v[10:11], v[88:89]
	v_pk_mul_f32 v[6:7], v[6:7], v[92:93]
	s_waitcnt lgkmcnt(0)
	v_pk_mul_f32 v[2:3], v[2:3], v[100:101]
	v_pk_mul_f32 v[0:1], v[0:1], v[98:99]
	v_pk_mul_f32 v[28:29], v[28:29], v[82:83]
	v_pk_mul_f32 v[24:25], v[24:25], v[86:87]
	v_pk_mul_f32 v[20:21], v[20:21], v[90:91]
	v_pk_mul_f32 v[30:31], v[30:31], v[84:85]
	v_pk_mul_f32 v[26:27], v[26:27], v[88:89]
	v_pk_mul_f32 v[22:23], v[22:23], v[92:93]
	v_pk_mul_f32 v[18:19], v[18:19], v[100:101]
	v_pk_mul_f32 v[16:17], v[16:17], v[98:99]
	v_pk_mul_f32 v[44:45], v[44:45], v[82:83]
	v_pk_mul_f32 v[40:41], v[40:41], v[86:87]
	v_pk_mul_f32 v[36:37], v[36:37], v[90:91]
	v_pk_mul_f32 v[46:47], v[46:47], v[84:85]
	v_pk_mul_f32 v[42:43], v[42:43], v[88:89]
	v_pk_mul_f32 v[38:39], v[38:39], v[92:93]
	v_pk_mul_f32 v[34:35], v[34:35], v[100:101]
	v_pk_mul_f32 v[32:33], v[32:33], v[98:99]
	v_pk_mul_f32 v[60:61], v[60:61], v[82:83]
	v_pk_mul_f32 v[56:57], v[56:57], v[86:87]
	v_pk_mul_f32 v[52:53], v[52:53], v[90:91]
	v_pk_mul_f32 v[62:63], v[62:63], v[84:85]
	v_pk_mul_f32 v[58:59], v[58:59], v[88:89]
	v_pk_mul_f32 v[54:55], v[54:55], v[92:93]
	v_pk_mul_f32 v[50:51], v[50:51], v[100:101]
	v_pk_mul_f32 v[48:49], v[48:49], v[98:99]
